# GEMM K-loops: leave the first MFMA group after the barrier free of LDS-DMA issue (DMAs in groups 12-15), barrier at group 11, A-first
# speedup vs baseline: 1.0032x; 1.0032x over previous
.LBB0_203:
	ds_read_b128 v[226:229], v157
	ds_read_b128 v[230:233], v158
	ds_read_b128 v[234:237], v159
	s_waitcnt lgkmcnt(5)
	v_mfma_f32_16x16x32_bf16 v[124:127], v[214:217], v[174:177], v[124:127]
	v_mfma_f32_16x16x32_bf16 v[120:123], v[214:217], v[178:181], v[120:123]
	v_mfma_f32_16x16x32_bf16 v[116:119], v[214:217], v[182:185], v[116:119]
	v_mfma_f32_16x16x32_bf16 v[112:115], v[214:217], v[186:189], v[112:115]
	ds_read_b128 v[238:241], v160
	s_waitcnt lgkmcnt(5)
	v_mfma_f32_16x16x32_bf16 v[108:111], v[218:221], v[174:177], v[108:111]
	v_mfma_f32_16x16x32_bf16 v[104:107], v[218:221], v[178:181], v[104:107]
	v_mfma_f32_16x16x32_bf16 v[100:103], v[218:221], v[182:185], v[100:103]
	v_mfma_f32_16x16x32_bf16 v[96:99], v[218:221], v[186:189], v[96:99]
	ds_read_b128 v[242:245], v161
	ds_read_b128 v[190:193], v153 offset:33792
	s_waitcnt lgkmcnt(6)
	v_mfma_f32_16x16x32_bf16 v[92:95], v[222:225], v[174:177], v[92:95]
	v_mfma_f32_16x16x32_bf16 v[88:91], v[222:225], v[178:181], v[88:91]
	v_mfma_f32_16x16x32_bf16 v[84:87], v[222:225], v[182:185], v[84:87]
	v_mfma_f32_16x16x32_bf16 v[80:83], v[222:225], v[186:189], v[80:83]
	ds_read_b128 v[214:217], v154 offset:1024
	ds_read_b128 v[194:197], v153 offset:35840
	s_waitcnt lgkmcnt(7)
	v_mfma_f32_16x16x32_bf16 v[76:79], v[226:229], v[174:177], v[76:79]
	v_mfma_f32_16x16x32_bf16 v[72:75], v[226:229], v[178:181], v[72:75]
	v_mfma_f32_16x16x32_bf16 v[68:71], v[226:229], v[182:185], v[68:71]
	v_mfma_f32_16x16x32_bf16 v[64:67], v[226:229], v[186:189], v[64:67]
	ds_read_b128 v[218:221], v155 offset:1024
	ds_read_b128 v[198:201], v153 offset:37888
	s_waitcnt lgkmcnt(8)
	v_mfma_f32_16x16x32_bf16 v[60:63], v[230:233], v[174:177], v[60:63]
	v_mfma_f32_16x16x32_bf16 v[56:59], v[230:233], v[178:181], v[56:59]
	v_mfma_f32_16x16x32_bf16 v[52:55], v[230:233], v[182:185], v[52:55]
	v_mfma_f32_16x16x32_bf16 v[48:51], v[230:233], v[186:189], v[48:51]
	ds_read_b128 v[222:225], v156 offset:1024
	ds_read_b128 v[210:213], v153 offset:39936
	s_waitcnt lgkmcnt(9)
	v_mfma_f32_16x16x32_bf16 v[44:47], v[234:237], v[174:177], v[44:47]
	v_mfma_f32_16x16x32_bf16 v[40:43], v[234:237], v[178:181], v[40:43]
	v_mfma_f32_16x16x32_bf16 v[36:39], v[234:237], v[182:185], v[36:39]
	v_mfma_f32_16x16x32_bf16 v[32:35], v[234:237], v[186:189], v[32:35]
	ds_read_b128 v[226:229], v157 offset:1024
	s_waitcnt lgkmcnt(9)
	v_mfma_f32_16x16x32_bf16 v[28:31], v[238:241], v[174:177], v[28:31]
	v_mfma_f32_16x16x32_bf16 v[24:27], v[238:241], v[178:181], v[24:27]
	v_mfma_f32_16x16x32_bf16 v[20:23], v[238:241], v[182:185], v[20:23]
	v_mfma_f32_16x16x32_bf16 v[16:19], v[238:241], v[186:189], v[16:19]
	ds_read_b128 v[230:233], v158 offset:1024
	s_waitcnt lgkmcnt(9)
	v_mfma_f32_16x16x32_bf16 v[12:15], v[242:245], v[174:177], v[12:15]
	v_mfma_f32_16x16x32_bf16 v[8:11], v[242:245], v[178:181], v[8:11]
	v_mfma_f32_16x16x32_bf16 v[4:7], v[242:245], v[182:185], v[4:7]
	v_mfma_f32_16x16x32_bf16 v[0:3], v[242:245], v[186:189], v[0:3]
	ds_read_b128 v[234:237], v159 offset:1024
	s_waitcnt lgkmcnt(3)
	v_mfma_f32_16x16x32_bf16 v[124:127], v[214:217], v[190:193], v[124:127]
	v_mfma_f32_16x16x32_bf16 v[120:123], v[214:217], v[194:197], v[120:123]
	v_mfma_f32_16x16x32_bf16 v[116:119], v[214:217], v[198:201], v[116:119]
	v_mfma_f32_16x16x32_bf16 v[112:115], v[214:217], v[210:213], v[112:115]
	ds_read_b128 v[238:241], v160 offset:1024
	v_mfma_f32_16x16x32_bf16 v[108:111], v[218:221], v[190:193], v[108:111]
	v_mfma_f32_16x16x32_bf16 v[104:107], v[218:221], v[194:197], v[104:107]
	v_mfma_f32_16x16x32_bf16 v[100:103], v[218:221], v[198:201], v[100:103]
	v_mfma_f32_16x16x32_bf16 v[96:99], v[218:221], v[210:213], v[96:99]
	ds_read_b128 v[242:245], v161 offset:1024
	v_mfma_f32_16x16x32_bf16 v[92:95], v[222:225], v[190:193], v[92:95]
	v_mfma_f32_16x16x32_bf16 v[88:91], v[222:225], v[194:197], v[88:91]
	v_mfma_f32_16x16x32_bf16 v[84:87], v[222:225], v[198:201], v[84:87]
	v_mfma_f32_16x16x32_bf16 v[80:83], v[222:225], v[210:213], v[80:83]
	s_waitcnt lgkmcnt(0)
	s_waitcnt vmcnt(0)
	s_barrier
	ds_read_b128 v[174:177], v162 offset:32768
	ds_read_b128 v[178:181], v162 offset:34816
	ds_read_b128 v[182:185], v162 offset:36864
	ds_read_b128 v[186:189], v162 offset:38912
	ds_read_b128 v[214:217], v170
	ds_read_b128 v[218:221], v171
	ds_read_b128 v[222:225], v163
	s_cmp_gt_u32 s23, 13
	s_cbranch_scc1 .Lg1_nostage0
	v_mfma_f32_16x16x32_bf16 v[76:79], v[226:229], v[190:193], v[76:79]
	v_mfma_f32_16x16x32_bf16 v[72:75], v[226:229], v[194:197], v[72:75]
	v_mfma_f32_16x16x32_bf16 v[68:71], v[226:229], v[198:201], v[68:71]
	v_mfma_f32_16x16x32_bf16 v[64:67], v[226:229], v[210:213], v[64:67]
	s_add_u32 m0, s24, 0x0
	v_mfma_f32_16x16x32_bf16 v[60:63], v[230:233], v[190:193], v[60:63]
	global_load_lds_dwordx4 v246, s[98:99]
	s_add_u32 m0, s24, 0x2000
	v_mfma_f32_16x16x32_bf16 v[56:59], v[230:233], v[194:197], v[56:59]
	global_load_lds_dwordx4 v247, s[98:99]
	v_mfma_f32_16x16x32_bf16 v[52:55], v[230:233], v[198:201], v[52:55]
	v_mfma_f32_16x16x32_bf16 v[48:51], v[230:233], v[210:213], v[48:51]
	s_add_u32 m0, s24, 0x4000
	v_mfma_f32_16x16x32_bf16 v[44:47], v[234:237], v[190:193], v[44:47]
	global_load_lds_dwordx4 v248, s[98:99]
	s_add_u32 m0, s24, 0x6000
	v_mfma_f32_16x16x32_bf16 v[40:43], v[234:237], v[194:197], v[40:43]
	global_load_lds_dwordx4 v249, s[98:99]
	v_mfma_f32_16x16x32_bf16 v[36:39], v[234:237], v[198:201], v[36:39]
	v_mfma_f32_16x16x32_bf16 v[32:35], v[234:237], v[210:213], v[32:35]
	s_add_u32 m0, s24, 0x8000
	v_mfma_f32_16x16x32_bf16 v[28:31], v[238:241], v[190:193], v[28:31]
	global_load_lds_dwordx4 v246, s[100:101]
	s_add_u32 m0, s24, 0xa000
	v_mfma_f32_16x16x32_bf16 v[24:27], v[238:241], v[194:197], v[24:27]
	global_load_lds_dwordx4 v247, s[100:101]
	v_mfma_f32_16x16x32_bf16 v[20:23], v[238:241], v[198:201], v[20:23]
	v_mfma_f32_16x16x32_bf16 v[16:19], v[238:241], v[210:213], v[16:19]
	s_add_u32 m0, s24, 0xc000
	v_mfma_f32_16x16x32_bf16 v[12:15], v[242:245], v[190:193], v[12:15]
	global_load_lds_dwordx4 v248, s[100:101]
	s_add_u32 m0, s24, 0xe000
	v_mfma_f32_16x16x32_bf16 v[8:11], v[242:245], v[194:197], v[8:11]
	global_load_lds_dwordx4 v249, s[100:101]
	v_mfma_f32_16x16x32_bf16 v[4:7], v[242:245], v[198:201], v[4:7]
	v_mfma_f32_16x16x32_bf16 v[0:3], v[242:245], v[210:213], v[0:3]
	s_add_u32 s98, s98, 0x80
	s_addc_u32 s99, s99, 0
	s_add_u32 s100, s100, 0x80
	s_addc_u32 s101, s101, 0
	s_branch .Lg1_half1

.Lg1_half1:
	ds_read_b128 v[226:229], v164
	ds_read_b128 v[230:233], v165
	ds_read_b128 v[234:237], v166
	s_waitcnt lgkmcnt(5)
	v_mfma_f32_16x16x32_bf16 v[124:127], v[214:217], v[174:177], v[124:127]
	v_mfma_f32_16x16x32_bf16 v[120:123], v[214:217], v[178:181], v[120:123]
	v_mfma_f32_16x16x32_bf16 v[116:119], v[214:217], v[182:185], v[116:119]
	v_mfma_f32_16x16x32_bf16 v[112:115], v[214:217], v[186:189], v[112:115]
	ds_read_b128 v[238:241], v167
	s_waitcnt lgkmcnt(5)
	v_mfma_f32_16x16x32_bf16 v[108:111], v[218:221], v[174:177], v[108:111]
	v_mfma_f32_16x16x32_bf16 v[104:107], v[218:221], v[178:181], v[104:107]
	v_mfma_f32_16x16x32_bf16 v[100:103], v[218:221], v[182:185], v[100:103]
	v_mfma_f32_16x16x32_bf16 v[96:99], v[218:221], v[186:189], v[96:99]
	ds_read_b128 v[242:245], v168
	ds_read_b128 v[190:193], v162 offset:33792
	s_waitcnt lgkmcnt(6)
	v_mfma_f32_16x16x32_bf16 v[92:95], v[222:225], v[174:177], v[92:95]
	v_mfma_f32_16x16x32_bf16 v[88:91], v[222:225], v[178:181], v[88:91]
	v_mfma_f32_16x16x32_bf16 v[84:87], v[222:225], v[182:185], v[84:87]
	v_mfma_f32_16x16x32_bf16 v[80:83], v[222:225], v[186:189], v[80:83]
	ds_read_b128 v[214:217], v170 offset:1024
	ds_read_b128 v[194:197], v162 offset:35840
	s_waitcnt lgkmcnt(7)
	v_mfma_f32_16x16x32_bf16 v[76:79], v[226:229], v[174:177], v[76:79]
	v_mfma_f32_16x16x32_bf16 v[72:75], v[226:229], v[178:181], v[72:75]
	v_mfma_f32_16x16x32_bf16 v[68:71], v[226:229], v[182:185], v[68:71]
	v_mfma_f32_16x16x32_bf16 v[64:67], v[226:229], v[186:189], v[64:67]
	ds_read_b128 v[218:221], v171 offset:1024
	ds_read_b128 v[198:201], v162 offset:37888
	s_waitcnt lgkmcnt(8)
	v_mfma_f32_16x16x32_bf16 v[60:63], v[230:233], v[174:177], v[60:63]
	v_mfma_f32_16x16x32_bf16 v[56:59], v[230:233], v[178:181], v[56:59]
	v_mfma_f32_16x16x32_bf16 v[52:55], v[230:233], v[182:185], v[52:55]
	v_mfma_f32_16x16x32_bf16 v[48:51], v[230:233], v[186:189], v[48:51]
	ds_read_b128 v[222:225], v163 offset:1024
	ds_read_b128 v[210:213], v162 offset:39936
	s_waitcnt lgkmcnt(9)
	v_mfma_f32_16x16x32_bf16 v[44:47], v[234:237], v[174:177], v[44:47]
	v_mfma_f32_16x16x32_bf16 v[40:43], v[234:237], v[178:181], v[40:43]
	v_mfma_f32_16x16x32_bf16 v[36:39], v[234:237], v[182:185], v[36:39]
	v_mfma_f32_16x16x32_bf16 v[32:35], v[234:237], v[186:189], v[32:35]
	ds_read_b128 v[226:229], v164 offset:1024
	s_waitcnt lgkmcnt(9)
	v_mfma_f32_16x16x32_bf16 v[28:31], v[238:241], v[174:177], v[28:31]
	v_mfma_f32_16x16x32_bf16 v[24:27], v[238:241], v[178:181], v[24:27]
	v_mfma_f32_16x16x32_bf16 v[20:23], v[238:241], v[182:185], v[20:23]
	v_mfma_f32_16x16x32_bf16 v[16:19], v[238:241], v[186:189], v[16:19]
	ds_read_b128 v[230:233], v165 offset:1024
	s_waitcnt lgkmcnt(9)
	v_mfma_f32_16x16x32_bf16 v[12:15], v[242:245], v[174:177], v[12:15]
	v_mfma_f32_16x16x32_bf16 v[8:11], v[242:245], v[178:181], v[8:11]
	v_mfma_f32_16x16x32_bf16 v[4:7], v[242:245], v[182:185], v[4:7]
	v_mfma_f32_16x16x32_bf16 v[0:3], v[242:245], v[186:189], v[0:3]
	ds_read_b128 v[234:237], v166 offset:1024
	s_waitcnt lgkmcnt(3)
	v_mfma_f32_16x16x32_bf16 v[124:127], v[214:217], v[190:193], v[124:127]
	v_mfma_f32_16x16x32_bf16 v[120:123], v[214:217], v[194:197], v[120:123]
	v_mfma_f32_16x16x32_bf16 v[116:119], v[214:217], v[198:201], v[116:119]
	v_mfma_f32_16x16x32_bf16 v[112:115], v[214:217], v[210:213], v[112:115]
	ds_read_b128 v[238:241], v167 offset:1024
	v_mfma_f32_16x16x32_bf16 v[108:111], v[218:221], v[190:193], v[108:111]
	v_mfma_f32_16x16x32_bf16 v[104:107], v[218:221], v[194:197], v[104:107]
	v_mfma_f32_16x16x32_bf16 v[100:103], v[218:221], v[198:201], v[100:103]
	v_mfma_f32_16x16x32_bf16 v[96:99], v[218:221], v[210:213], v[96:99]
	ds_read_b128 v[242:245], v168 offset:1024
	v_mfma_f32_16x16x32_bf16 v[92:95], v[222:225], v[190:193], v[92:95]
	v_mfma_f32_16x16x32_bf16 v[88:91], v[222:225], v[194:197], v[88:91]
	v_mfma_f32_16x16x32_bf16 v[84:87], v[222:225], v[198:201], v[84:87]
	v_mfma_f32_16x16x32_bf16 v[80:83], v[222:225], v[210:213], v[80:83]
	s_waitcnt lgkmcnt(0)
	s_waitcnt vmcnt(0)
	s_barrier
	s_cmp_gt_u32 s23, 13
	s_cbranch_scc1 .Lg1_last
	ds_read_b128 v[174:177], v153 offset:32768
	ds_read_b128 v[178:181], v153 offset:34816
	ds_read_b128 v[182:185], v153 offset:36864
	ds_read_b128 v[186:189], v153 offset:38912
	ds_read_b128 v[214:217], v154
	ds_read_b128 v[218:221], v155
	ds_read_b128 v[222:225], v156
	v_mfma_f32_16x16x32_bf16 v[76:79], v[226:229], v[190:193], v[76:79]
	v_mfma_f32_16x16x32_bf16 v[72:75], v[226:229], v[194:197], v[72:75]
	v_mfma_f32_16x16x32_bf16 v[68:71], v[226:229], v[198:201], v[68:71]
	v_mfma_f32_16x16x32_bf16 v[64:67], v[226:229], v[210:213], v[64:67]
	s_add_u32 m0, s24, 0x10400
	v_mfma_f32_16x16x32_bf16 v[60:63], v[230:233], v[190:193], v[60:63]
	global_load_lds_dwordx4 v246, s[98:99]
	s_add_u32 m0, s24, 0x12400
	v_mfma_f32_16x16x32_bf16 v[56:59], v[230:233], v[194:197], v[56:59]
	global_load_lds_dwordx4 v247, s[98:99]
	v_mfma_f32_16x16x32_bf16 v[52:55], v[230:233], v[198:201], v[52:55]
	v_mfma_f32_16x16x32_bf16 v[48:51], v[230:233], v[210:213], v[48:51]
	s_add_u32 m0, s24, 0x14400
	v_mfma_f32_16x16x32_bf16 v[44:47], v[234:237], v[190:193], v[44:47]
	global_load_lds_dwordx4 v248, s[98:99]
	s_add_u32 m0, s24, 0x16400
	v_mfma_f32_16x16x32_bf16 v[40:43], v[234:237], v[194:197], v[40:43]
	global_load_lds_dwordx4 v249, s[98:99]
	v_mfma_f32_16x16x32_bf16 v[36:39], v[234:237], v[198:201], v[36:39]
	v_mfma_f32_16x16x32_bf16 v[32:35], v[234:237], v[210:213], v[32:35]
	s_add_u32 m0, s24, 0x18400
	v_mfma_f32_16x16x32_bf16 v[28:31], v[238:241], v[190:193], v[28:31]
	global_load_lds_dwordx4 v246, s[100:101]
	s_add_u32 m0, s24, 0x1a400
	v_mfma_f32_16x16x32_bf16 v[24:27], v[238:241], v[194:197], v[24:27]
	global_load_lds_dwordx4 v247, s[100:101]
	v_mfma_f32_16x16x32_bf16 v[20:23], v[238:241], v[198:201], v[20:23]
	v_mfma_f32_16x16x32_bf16 v[16:19], v[238:241], v[210:213], v[16:19]
	s_add_u32 m0, s24, 0x1c400
	v_mfma_f32_16x16x32_bf16 v[12:15], v[242:245], v[190:193], v[12:15]
	global_load_lds_dwordx4 v248, s[100:101]
	s_add_u32 m0, s24, 0x1e400
	v_mfma_f32_16x16x32_bf16 v[8:11], v[242:245], v[194:197], v[8:11]
	global_load_lds_dwordx4 v249, s[100:101]
	v_mfma_f32_16x16x32_bf16 v[4:7], v[242:245], v[198:201], v[4:7]
	v_mfma_f32_16x16x32_bf16 v[0:3], v[242:245], v[210:213], v[0:3]
	s_add_u32 s98, s98, 0x80
	s_addc_u32 s99, s99, 0
	s_add_u32 s100, s100, 0x80
	s_addc_u32 s101, s101, 0
	s_add_i32 s23, s23, 2
	s_branch .LBB0_203

.LBB0_1788:
	ds_read_b128 v[222:225], v159
	ds_read_b128 v[226:229], v160
	ds_read_b128 v[230:233], v161
	s_waitcnt lgkmcnt(5)
	v_mfma_f32_16x16x32_bf16 v[124:127], v[210:213], v[178:181], v[124:127]
	v_mfma_f32_16x16x32_bf16 v[120:123], v[210:213], v[182:185], v[120:123]
	v_mfma_f32_16x16x32_bf16 v[116:119], v[210:213], v[186:189], v[116:119]
	v_mfma_f32_16x16x32_bf16 v[112:115], v[210:213], v[190:193], v[112:115]
	ds_read_b128 v[234:237], v162
	s_waitcnt lgkmcnt(5)
	v_mfma_f32_16x16x32_bf16 v[108:111], v[214:217], v[178:181], v[108:111]
	v_mfma_f32_16x16x32_bf16 v[104:107], v[214:217], v[182:185], v[104:107]
	v_mfma_f32_16x16x32_bf16 v[100:103], v[214:217], v[186:189], v[100:103]
	v_mfma_f32_16x16x32_bf16 v[96:99], v[214:217], v[190:193], v[96:99]
	ds_read_b128 v[238:241], v163
	ds_read_b128 v[194:197], v155 offset:33792
	s_waitcnt lgkmcnt(6)
	v_mfma_f32_16x16x32_bf16 v[92:95], v[218:221], v[178:181], v[92:95]
	v_mfma_f32_16x16x32_bf16 v[88:91], v[218:221], v[182:185], v[88:91]
	v_mfma_f32_16x16x32_bf16 v[84:87], v[218:221], v[186:189], v[84:87]
	v_mfma_f32_16x16x32_bf16 v[80:83], v[218:221], v[190:193], v[80:83]
	ds_read_b128 v[210:213], v156 offset:1024
	ds_read_b128 v[198:201], v155 offset:35840
	s_waitcnt lgkmcnt(7)
	v_mfma_f32_16x16x32_bf16 v[76:79], v[222:225], v[178:181], v[76:79]
	v_mfma_f32_16x16x32_bf16 v[72:75], v[222:225], v[182:185], v[72:75]
	v_mfma_f32_16x16x32_bf16 v[68:71], v[222:225], v[186:189], v[68:71]
	v_mfma_f32_16x16x32_bf16 v[64:67], v[222:225], v[190:193], v[64:67]
	ds_read_b128 v[214:217], v157 offset:1024
	ds_read_b128 v[202:205], v155 offset:37888
	s_waitcnt lgkmcnt(8)
	v_mfma_f32_16x16x32_bf16 v[60:63], v[226:229], v[178:181], v[60:63]
	v_mfma_f32_16x16x32_bf16 v[56:59], v[226:229], v[182:185], v[56:59]
	v_mfma_f32_16x16x32_bf16 v[52:55], v[226:229], v[186:189], v[52:55]
	v_mfma_f32_16x16x32_bf16 v[48:51], v[226:229], v[190:193], v[48:51]
	ds_read_b128 v[218:221], v158 offset:1024
	ds_read_b128 v[206:209], v155 offset:39936
	s_waitcnt lgkmcnt(9)
	v_mfma_f32_16x16x32_bf16 v[44:47], v[230:233], v[178:181], v[44:47]
	v_mfma_f32_16x16x32_bf16 v[40:43], v[230:233], v[182:185], v[40:43]
	v_mfma_f32_16x16x32_bf16 v[36:39], v[230:233], v[186:189], v[36:39]
	v_mfma_f32_16x16x32_bf16 v[32:35], v[230:233], v[190:193], v[32:35]
	ds_read_b128 v[222:225], v159 offset:1024
	s_waitcnt lgkmcnt(9)
	v_mfma_f32_16x16x32_bf16 v[28:31], v[234:237], v[178:181], v[28:31]
	v_mfma_f32_16x16x32_bf16 v[24:27], v[234:237], v[182:185], v[24:27]
	v_mfma_f32_16x16x32_bf16 v[20:23], v[234:237], v[186:189], v[20:23]
	v_mfma_f32_16x16x32_bf16 v[16:19], v[234:237], v[190:193], v[16:19]
	ds_read_b128 v[226:229], v160 offset:1024
	s_waitcnt lgkmcnt(9)
	v_mfma_f32_16x16x32_bf16 v[12:15], v[238:241], v[178:181], v[12:15]
	v_mfma_f32_16x16x32_bf16 v[8:11], v[238:241], v[182:185], v[8:11]
	v_mfma_f32_16x16x32_bf16 v[4:7], v[238:241], v[186:189], v[4:7]
	v_mfma_f32_16x16x32_bf16 v[0:3], v[238:241], v[190:193], v[0:3]
	ds_read_b128 v[230:233], v161 offset:1024
	s_waitcnt lgkmcnt(3)
	v_mfma_f32_16x16x32_bf16 v[124:127], v[210:213], v[194:197], v[124:127]
	v_mfma_f32_16x16x32_bf16 v[120:123], v[210:213], v[198:201], v[120:123]
	v_mfma_f32_16x16x32_bf16 v[116:119], v[210:213], v[202:205], v[116:119]
	v_mfma_f32_16x16x32_bf16 v[112:115], v[210:213], v[206:209], v[112:115]
	ds_read_b128 v[234:237], v162 offset:1024
	v_mfma_f32_16x16x32_bf16 v[108:111], v[214:217], v[194:197], v[108:111]
	v_mfma_f32_16x16x32_bf16 v[104:107], v[214:217], v[198:201], v[104:107]
	v_mfma_f32_16x16x32_bf16 v[100:103], v[214:217], v[202:205], v[100:103]
	v_mfma_f32_16x16x32_bf16 v[96:99], v[214:217], v[206:209], v[96:99]
	ds_read_b128 v[238:241], v163 offset:1024
	v_mfma_f32_16x16x32_bf16 v[92:95], v[218:221], v[194:197], v[92:95]
	v_mfma_f32_16x16x32_bf16 v[88:91], v[218:221], v[198:201], v[88:91]
	v_mfma_f32_16x16x32_bf16 v[84:87], v[218:221], v[202:205], v[84:87]
	v_mfma_f32_16x16x32_bf16 v[80:83], v[218:221], v[206:209], v[80:83]
	s_waitcnt lgkmcnt(0)
	s_waitcnt vmcnt(0)
	s_barrier
	ds_read_b128 v[178:181], v164 offset:32768
	ds_read_b128 v[182:185], v164 offset:34816
	ds_read_b128 v[186:189], v164 offset:36864
	ds_read_b128 v[190:193], v164 offset:38912
	ds_read_b128 v[210:213], v172
	ds_read_b128 v[214:217], v173
	ds_read_b128 v[218:221], v165
	s_cmp_gt_u32 s1, 13
	s_cbranch_scc1 .Lg4_nostage0
	v_mfma_f32_16x16x32_bf16 v[76:79], v[222:225], v[194:197], v[76:79]
	v_mfma_f32_16x16x32_bf16 v[72:75], v[222:225], v[198:201], v[72:75]
	v_mfma_f32_16x16x32_bf16 v[68:71], v[222:225], v[202:205], v[68:71]
	v_mfma_f32_16x16x32_bf16 v[64:67], v[222:225], v[206:209], v[64:67]
	s_add_u32 m0, s45, 0x0
	v_mfma_f32_16x16x32_bf16 v[60:63], v[226:229], v[194:197], v[60:63]
	global_load_lds_dwordx4 v174, s[98:99]
	s_add_u32 m0, s45, 0x2000
	v_mfma_f32_16x16x32_bf16 v[56:59], v[226:229], v[198:201], v[56:59]
	global_load_lds_dwordx4 v175, s[98:99]
	v_mfma_f32_16x16x32_bf16 v[52:55], v[226:229], v[202:205], v[52:55]
	v_mfma_f32_16x16x32_bf16 v[48:51], v[226:229], v[206:209], v[48:51]
	s_add_u32 m0, s45, 0x4000
	v_mfma_f32_16x16x32_bf16 v[44:47], v[230:233], v[194:197], v[44:47]
	global_load_lds_dwordx4 v176, s[98:99]
	s_add_u32 m0, s45, 0x6000
	v_mfma_f32_16x16x32_bf16 v[40:43], v[230:233], v[198:201], v[40:43]
	global_load_lds_dwordx4 v177, s[98:99]
	v_mfma_f32_16x16x32_bf16 v[36:39], v[230:233], v[202:205], v[36:39]
	v_mfma_f32_16x16x32_bf16 v[32:35], v[230:233], v[206:209], v[32:35]
	s_add_u32 m0, s45, 0x8000
	v_mfma_f32_16x16x32_bf16 v[28:31], v[234:237], v[194:197], v[28:31]
	global_load_lds_dwordx4 v174, s[100:101]
	s_add_u32 m0, s45, 0xa000
	v_mfma_f32_16x16x32_bf16 v[24:27], v[234:237], v[198:201], v[24:27]
	global_load_lds_dwordx4 v175, s[100:101]
	v_mfma_f32_16x16x32_bf16 v[20:23], v[234:237], v[202:205], v[20:23]
	v_mfma_f32_16x16x32_bf16 v[16:19], v[234:237], v[206:209], v[16:19]
	s_add_u32 m0, s45, 0xc000
	v_mfma_f32_16x16x32_bf16 v[12:15], v[238:241], v[194:197], v[12:15]
	global_load_lds_dwordx4 v176, s[100:101]
	s_add_u32 m0, s45, 0xe000
	v_mfma_f32_16x16x32_bf16 v[8:11], v[238:241], v[198:201], v[8:11]
	global_load_lds_dwordx4 v177, s[100:101]
	v_mfma_f32_16x16x32_bf16 v[4:7], v[238:241], v[202:205], v[4:7]
	v_mfma_f32_16x16x32_bf16 v[0:3], v[238:241], v[206:209], v[0:3]
	s_add_u32 s98, s98, 0x80
	s_addc_u32 s99, s99, 0
	s_add_u32 s100, s100, 0x80
	s_addc_u32 s101, s101, 0
	s_branch .Lg4_half1

.Lg4_half1:
	ds_read_b128 v[222:225], v166
	ds_read_b128 v[226:229], v167
	ds_read_b128 v[230:233], v168
	s_waitcnt lgkmcnt(5)
	v_mfma_f32_16x16x32_bf16 v[124:127], v[210:213], v[178:181], v[124:127]
	v_mfma_f32_16x16x32_bf16 v[120:123], v[210:213], v[182:185], v[120:123]
	v_mfma_f32_16x16x32_bf16 v[116:119], v[210:213], v[186:189], v[116:119]
	v_mfma_f32_16x16x32_bf16 v[112:115], v[210:213], v[190:193], v[112:115]
	ds_read_b128 v[234:237], v169
	s_waitcnt lgkmcnt(5)
	v_mfma_f32_16x16x32_bf16 v[108:111], v[214:217], v[178:181], v[108:111]
	v_mfma_f32_16x16x32_bf16 v[104:107], v[214:217], v[182:185], v[104:107]
	v_mfma_f32_16x16x32_bf16 v[100:103], v[214:217], v[186:189], v[100:103]
	v_mfma_f32_16x16x32_bf16 v[96:99], v[214:217], v[190:193], v[96:99]
	ds_read_b128 v[238:241], v170
	ds_read_b128 v[194:197], v164 offset:33792
	s_waitcnt lgkmcnt(6)
	v_mfma_f32_16x16x32_bf16 v[92:95], v[218:221], v[178:181], v[92:95]
	v_mfma_f32_16x16x32_bf16 v[88:91], v[218:221], v[182:185], v[88:91]
	v_mfma_f32_16x16x32_bf16 v[84:87], v[218:221], v[186:189], v[84:87]
	v_mfma_f32_16x16x32_bf16 v[80:83], v[218:221], v[190:193], v[80:83]
	ds_read_b128 v[210:213], v172 offset:1024
	ds_read_b128 v[198:201], v164 offset:35840
	s_waitcnt lgkmcnt(7)
	v_mfma_f32_16x16x32_bf16 v[76:79], v[222:225], v[178:181], v[76:79]
	v_mfma_f32_16x16x32_bf16 v[72:75], v[222:225], v[182:185], v[72:75]
	v_mfma_f32_16x16x32_bf16 v[68:71], v[222:225], v[186:189], v[68:71]
	v_mfma_f32_16x16x32_bf16 v[64:67], v[222:225], v[190:193], v[64:67]
	ds_read_b128 v[214:217], v173 offset:1024
	ds_read_b128 v[202:205], v164 offset:37888
	s_waitcnt lgkmcnt(8)
	v_mfma_f32_16x16x32_bf16 v[60:63], v[226:229], v[178:181], v[60:63]
	v_mfma_f32_16x16x32_bf16 v[56:59], v[226:229], v[182:185], v[56:59]
	v_mfma_f32_16x16x32_bf16 v[52:55], v[226:229], v[186:189], v[52:55]
	v_mfma_f32_16x16x32_bf16 v[48:51], v[226:229], v[190:193], v[48:51]
	ds_read_b128 v[218:221], v165 offset:1024
	ds_read_b128 v[206:209], v164 offset:39936
	s_waitcnt lgkmcnt(9)
	v_mfma_f32_16x16x32_bf16 v[44:47], v[230:233], v[178:181], v[44:47]
	v_mfma_f32_16x16x32_bf16 v[40:43], v[230:233], v[182:185], v[40:43]
	v_mfma_f32_16x16x32_bf16 v[36:39], v[230:233], v[186:189], v[36:39]
	v_mfma_f32_16x16x32_bf16 v[32:35], v[230:233], v[190:193], v[32:35]
	ds_read_b128 v[222:225], v166 offset:1024
	s_waitcnt lgkmcnt(9)
	v_mfma_f32_16x16x32_bf16 v[28:31], v[234:237], v[178:181], v[28:31]
	v_mfma_f32_16x16x32_bf16 v[24:27], v[234:237], v[182:185], v[24:27]
	v_mfma_f32_16x16x32_bf16 v[20:23], v[234:237], v[186:189], v[20:23]
	v_mfma_f32_16x16x32_bf16 v[16:19], v[234:237], v[190:193], v[16:19]
	ds_read_b128 v[226:229], v167 offset:1024
	s_waitcnt lgkmcnt(9)
	v_mfma_f32_16x16x32_bf16 v[12:15], v[238:241], v[178:181], v[12:15]
	v_mfma_f32_16x16x32_bf16 v[8:11], v[238:241], v[182:185], v[8:11]
	v_mfma_f32_16x16x32_bf16 v[4:7], v[238:241], v[186:189], v[4:7]
	v_mfma_f32_16x16x32_bf16 v[0:3], v[238:241], v[190:193], v[0:3]
	ds_read_b128 v[230:233], v168 offset:1024
	s_waitcnt lgkmcnt(3)
	v_mfma_f32_16x16x32_bf16 v[124:127], v[210:213], v[194:197], v[124:127]
	v_mfma_f32_16x16x32_bf16 v[120:123], v[210:213], v[198:201], v[120:123]
	v_mfma_f32_16x16x32_bf16 v[116:119], v[210:213], v[202:205], v[116:119]
	v_mfma_f32_16x16x32_bf16 v[112:115], v[210:213], v[206:209], v[112:115]
	ds_read_b128 v[234:237], v169 offset:1024
	v_mfma_f32_16x16x32_bf16 v[108:111], v[214:217], v[194:197], v[108:111]
	v_mfma_f32_16x16x32_bf16 v[104:107], v[214:217], v[198:201], v[104:107]
	v_mfma_f32_16x16x32_bf16 v[100:103], v[214:217], v[202:205], v[100:103]
	v_mfma_f32_16x16x32_bf16 v[96:99], v[214:217], v[206:209], v[96:99]
	ds_read_b128 v[238:241], v170 offset:1024
	v_mfma_f32_16x16x32_bf16 v[92:95], v[218:221], v[194:197], v[92:95]
	v_mfma_f32_16x16x32_bf16 v[88:91], v[218:221], v[198:201], v[88:91]
	v_mfma_f32_16x16x32_bf16 v[84:87], v[218:221], v[202:205], v[84:87]
	v_mfma_f32_16x16x32_bf16 v[80:83], v[218:221], v[206:209], v[80:83]
	s_waitcnt lgkmcnt(0)
	s_waitcnt vmcnt(0)
	s_barrier
	s_cmp_gt_u32 s1, 13
	s_cbranch_scc1 .Lg4_last
	ds_read_b128 v[178:181], v155 offset:32768
	ds_read_b128 v[182:185], v155 offset:34816
	ds_read_b128 v[186:189], v155 offset:36864
	ds_read_b128 v[190:193], v155 offset:38912
	ds_read_b128 v[210:213], v156
	ds_read_b128 v[214:217], v157
	ds_read_b128 v[218:221], v158
	v_mfma_f32_16x16x32_bf16 v[76:79], v[222:225], v[194:197], v[76:79]
	v_mfma_f32_16x16x32_bf16 v[72:75], v[222:225], v[198:201], v[72:75]
	v_mfma_f32_16x16x32_bf16 v[68:71], v[222:225], v[202:205], v[68:71]
	v_mfma_f32_16x16x32_bf16 v[64:67], v[222:225], v[206:209], v[64:67]
	s_add_u32 m0, s45, 0x10400
	v_mfma_f32_16x16x32_bf16 v[60:63], v[226:229], v[194:197], v[60:63]
	global_load_lds_dwordx4 v174, s[98:99]
	s_add_u32 m0, s45, 0x12400
	v_mfma_f32_16x16x32_bf16 v[56:59], v[226:229], v[198:201], v[56:59]
	global_load_lds_dwordx4 v175, s[98:99]
	v_mfma_f32_16x16x32_bf16 v[52:55], v[226:229], v[202:205], v[52:55]
	v_mfma_f32_16x16x32_bf16 v[48:51], v[226:229], v[206:209], v[48:51]
	s_add_u32 m0, s45, 0x14400
	v_mfma_f32_16x16x32_bf16 v[44:47], v[230:233], v[194:197], v[44:47]
	global_load_lds_dwordx4 v176, s[98:99]
	s_add_u32 m0, s45, 0x16400
	v_mfma_f32_16x16x32_bf16 v[40:43], v[230:233], v[198:201], v[40:43]
	global_load_lds_dwordx4 v177, s[98:99]
	v_mfma_f32_16x16x32_bf16 v[36:39], v[230:233], v[202:205], v[36:39]
	v_mfma_f32_16x16x32_bf16 v[32:35], v[230:233], v[206:209], v[32:35]
	s_add_u32 m0, s45, 0x18400
	v_mfma_f32_16x16x32_bf16 v[28:31], v[234:237], v[194:197], v[28:31]
	global_load_lds_dwordx4 v174, s[100:101]
	s_add_u32 m0, s45, 0x1a400
	v_mfma_f32_16x16x32_bf16 v[24:27], v[234:237], v[198:201], v[24:27]
	global_load_lds_dwordx4 v175, s[100:101]
	v_mfma_f32_16x16x32_bf16 v[20:23], v[234:237], v[202:205], v[20:23]
	v_mfma_f32_16x16x32_bf16 v[16:19], v[234:237], v[206:209], v[16:19]
	s_add_u32 m0, s45, 0x1c400
	v_mfma_f32_16x16x32_bf16 v[12:15], v[238:241], v[194:197], v[12:15]
	global_load_lds_dwordx4 v176, s[100:101]
	s_add_u32 m0, s45, 0x1e400
	v_mfma_f32_16x16x32_bf16 v[8:11], v[238:241], v[198:201], v[8:11]
	global_load_lds_dwordx4 v177, s[100:101]
	v_mfma_f32_16x16x32_bf16 v[4:7], v[238:241], v[202:205], v[4:7]
	v_mfma_f32_16x16x32_bf16 v[0:3], v[238:241], v[206:209], v[0:3]
	s_add_u32 s98, s98, 0x80
	s_addc_u32 s99, s99, 0
	s_add_u32 s100, s100, 0x80
	s_addc_u32 s101, s101, 0
	s_add_i32 s1, s1, 2
	s_branch .LBB0_1788
